# dense attention: query-block-0 row-sum MFMAs issued together with the PV cluster
# baseline (speedup 1.0000x reference)
.LBB0_1279:
	v_fma_f32 v132, v132, s35, -v2
	v_fma_f32 v133, v133, s35, -v2
	v_fma_f32 v134, v134, s35, -v2
	v_fma_f32 v135, v135, s35, -v2
	v_fma_f32 v124, v124, s35, -v2
	v_fma_f32 v3, v136, s35, -v2
	v_fma_f32 v136, v137, s35, -v2
	v_fma_f32 v137, v138, s35, -v2
	v_fma_f32 v138, v139, s35, -v2
	v_exp_f32_e32 v132, v132
	v_exp_f32_e32 v133, v133
	v_exp_f32_e32 v134, v134
	v_exp_f32_e32 v135, v135
	v_exp_f32_e32 v139, v124
	v_fma_f32 v124, v125, s35, -v2
	v_fma_f32 v128, v128, s35, -v2
	v_fma_f32 v129, v129, s35, -v2
	v_fma_f32 v130, v130, s35, -v2
	v_fma_f32 v131, v131, s35, -v2
	v_exp_f32_e32 v163, v124
	v_fma_f32 v124, v126, s35, -v2
	v_fma_f32 v2, v127, s35, -v2
	v_exp_f32_e32 v3, v3
	v_exp_f32_e32 v136, v136
	v_exp_f32_e32 v128, v128
	v_exp_f32_e32 v129, v129
	v_exp_f32_e32 v130, v130
	v_exp_f32_e32 v131, v131
	v_exp_f32_e32 v164, v124
	v_exp_f32_e32 v2, v2
	s_mov_b32 s66, s64
	s_mov_b32 s67, s64
	v_cvt_pk_bf16_f32 v126, v132, v133
	v_cvt_pk_bf16_f32 v127, v134, v135
	s_mov_b32 s65, s64
	v_mov_b64_e32 v[134:135], s[66:67]
	v_exp_f32_e32 v137, v137
	v_exp_f32_e32 v138, v138
	v_mov_b64_e32 v[132:133], s[64:65]
	v_cvt_pk_bf16_f32 v124, v3, v136
	v_cvt_pk_bf16_f32 v128, v128, v129
	v_cvt_pk_bf16_f32 v129, v130, v131
	v_cvt_pk_bf16_f32 v131, v164, v2
	v_max_f32_e32 v2, v121, v121
	v_max_f32_e32 v3, v120, v120
	v_max_f32_e32 v2, v3, v2
	v_max3_f32 v2, v2, v122, v123
	v_cvt_pk_bf16_f32 v125, v137, v138
	v_max3_f32 v2, v2, v116, v117
	v_max3_f32 v2, v2, v118, v119
	v_max3_f32 v2, v2, v112, v113
	v_max3_f32 v2, v2, v114, v115
	v_cvt_pk_bf16_f32 v130, v139, v163
	v_max3_f32 v2, v2, v108, v109
	v_max3_f32 v2, v2, v110, v111
	v_mul_f32_e32 v2, 0x3e38aa3b, v2
	v_max_f32_e32 v3, v159, v159
	v_max_f32_e32 v2, v3, v2
	v_cmp_gt_f32_e32 vcc, v2, v159
	s_cbranch_vccz .LBB0_1284
	v_cmp_lt_i32_e32 vcc, v175, v173
	s_nop 1
	v_cndmask_b32_e32 v3, v172, v175, vcc
	v_lshlrev_b32_e32 v3, 2, v3
	ds_bpermute_b32 v3, v3, v2
	v_cmp_lt_i32_e32 vcc, v174, v173
	v_max_f32_e32 v2, v2, v2
	s_waitcnt lgkmcnt(0)
	v_max_f32_e32 v3, v3, v3
	v_cndmask_b32_e32 v132, v172, v174, vcc
	v_max_f32_e32 v2, v2, v3
	v_lshlrev_b32_e32 v3, 2, v132
	ds_bpermute_b32 v3, v3, v2
	s_waitcnt lgkmcnt(0)
	v_max_f32_e32 v3, v3, v3
	v_max_f32_e32 v133, v2, v3
	v_sub_f32_e32 v2, v159, v133
	v_exp_f32_e32 v132, v2
	v_mov_b32_e32 v159, v133
	v_mov_b64_e32 v[2:3], v[158:159]
	v_pk_mul_f32 v[62:63], v[62:63], v[132:133] op_sel_hi:[1,0]
	v_pk_mul_f32 v[60:61], v[60:61], v[132:133] op_sel_hi:[1,0]
	v_pk_mul_f32 v[50:51], v[50:51], v[132:133] op_sel_hi:[1,0]
	v_pk_mul_f32 v[48:49], v[48:49], v[132:133] op_sel_hi:[1,0]
	v_pk_mul_f32 v[46:47], v[46:47], v[132:133] op_sel_hi:[1,0]
	v_pk_mul_f32 v[44:45], v[44:45], v[132:133] op_sel_hi:[1,0]
	v_pk_mul_f32 v[42:43], v[42:43], v[132:133] op_sel_hi:[1,0]
	v_pk_mul_f32 v[40:41], v[40:41], v[132:133] op_sel_hi:[1,0]
	v_pk_mul_f32 v[66:67], v[66:67], v[132:133] op_sel_hi:[1,0]
	v_pk_mul_f32 v[64:65], v[64:65], v[132:133] op_sel_hi:[1,0]
	s_branch .LBB0_1285

.LBB0_1282:
	v_fma_f32 v132, v132, s35, -v2
	v_fma_f32 v133, v133, s35, -v2
	v_fma_f32 v134, v134, s35, -v2
	v_fma_f32 v135, v135, s35, -v2
	v_fma_f32 v124, v124, s35, -v2
	v_fma_f32 v0, v136, s35, -v2
	v_fma_f32 v136, v138, s35, -v2
	v_exp_f32_e32 v132, v132
	v_exp_f32_e32 v133, v133
	v_exp_f32_e32 v134, v134
	v_exp_f32_e32 v135, v135
	v_exp_f32_e32 v138, v124
	v_fma_f32 v124, v125, s35, -v2
	v_fma_f32 v3, v137, s35, -v2
	v_fma_f32 v137, v139, s35, -v2
	v_fma_f32 v128, v128, s35, -v2
	v_fma_f32 v129, v129, s35, -v2
	v_fma_f32 v130, v130, s35, -v2
	v_fma_f32 v131, v131, s35, -v2
	v_exp_f32_e32 v139, v124
	v_fma_f32 v124, v126, s35, -v2
	v_fma_f32 v2, v127, s35, -v2
	v_exp_f32_e32 v0, v0
	v_exp_f32_e32 v3, v3
	v_exp_f32_e32 v128, v128
	v_exp_f32_e32 v129, v129
	v_exp_f32_e32 v130, v130
	v_exp_f32_e32 v131, v131
	v_exp_f32_e32 v149, v124
	v_exp_f32_e32 v2, v2
	s_mov_b32 s66, s64
	s_mov_b32 s67, s64
	v_cvt_pk_bf16_f32 v126, v132, v133
	v_cvt_pk_bf16_f32 v127, v134, v135
	s_mov_b32 s65, s64
	v_mov_b64_e32 v[134:135], s[66:67]
	v_exp_f32_e32 v136, v136
	v_exp_f32_e32 v137, v137
	v_mov_b64_e32 v[132:133], s[64:65]
	v_cvt_pk_bf16_f32 v124, v0, v3
	v_cvt_pk_bf16_f32 v128, v128, v129
	v_cvt_pk_bf16_f32 v129, v130, v131
	v_cvt_pk_bf16_f32 v131, v149, v2
	v_max_f32_e32 v0, v121, v121
	v_max_f32_e32 v2, v120, v120
	v_max_f32_e32 v0, v2, v0
	v_max3_f32 v0, v0, v122, v123
	v_cvt_pk_bf16_f32 v125, v136, v137
	v_max3_f32 v0, v0, v116, v117
	v_max3_f32 v0, v0, v118, v119
	v_max3_f32 v0, v0, v112, v113
	v_max3_f32 v0, v0, v114, v115
	v_cvt_pk_bf16_f32 v130, v138, v139
	v_max3_f32 v0, v0, v108, v109
	v_max3_f32 v0, v0, v110, v111
	v_mul_f32_e32 v0, 0x3e38aa3b, v0
	v_max_f32_e32 v2, v159, v159
	v_max_f32_e32 v0, v2, v0
	v_cmp_gt_f32_e32 vcc, v0, v159
	s_cbranch_vccz .LBB0_1290
	v_cmp_lt_i32_e32 vcc, v175, v173
	s_nop 1
	v_cndmask_b32_e32 v2, v172, v175, vcc
	v_lshlrev_b32_e32 v2, 2, v2
	ds_bpermute_b32 v2, v2, v0
	v_cmp_lt_i32_e32 vcc, v174, v173
	v_max_f32_e32 v0, v0, v0
	s_waitcnt lgkmcnt(0)
	v_max_f32_e32 v2, v2, v2
	v_cndmask_b32_e32 v3, v172, v174, vcc
	v_max_f32_e32 v0, v0, v2
	v_lshlrev_b32_e32 v2, 2, v3
	ds_bpermute_b32 v2, v2, v0
	s_waitcnt lgkmcnt(0)
	v_max_f32_e32 v2, v2, v2
	v_max_f32_e32 v132, v0, v2
	v_sub_f32_e32 v0, v159, v132
	v_exp_f32_e32 v0, v0
	v_mov_b32_e32 v159, v132
	v_mov_b64_e32 v[2:3], v[158:159]
	v_pk_mul_f32 v[62:63], v[62:63], v[0:1] op_sel_hi:[1,0]
	v_pk_mul_f32 v[60:61], v[60:61], v[0:1] op_sel_hi:[1,0]
	v_pk_mul_f32 v[50:51], v[50:51], v[0:1] op_sel_hi:[1,0]
	v_pk_mul_f32 v[48:49], v[48:49], v[0:1] op_sel_hi:[1,0]
	v_pk_mul_f32 v[46:47], v[46:47], v[0:1] op_sel_hi:[1,0]
	v_pk_mul_f32 v[44:45], v[44:45], v[0:1] op_sel_hi:[1,0]
	v_pk_mul_f32 v[42:43], v[42:43], v[0:1] op_sel_hi:[1,0]
	v_pk_mul_f32 v[40:41], v[40:41], v[0:1] op_sel_hi:[1,0]
	v_pk_mul_f32 v[66:67], v[66:67], v[0:1] op_sel_hi:[1,0]
	v_pk_mul_f32 v[64:65], v[64:65], v[0:1] op_sel_hi:[1,0]
	s_branch .LBB0_1291

.LBB0_1285:
	v_fma_f32 v112, v112, s35, -v159
	v_exp_f32_e32 v132, v112
	v_fma_f32 v112, v113, s35, -v159
	v_exp_f32_e32 v133, v112
	v_fma_f32 v112, v114, s35, -v159
	v_exp_f32_e32 v134, v112
	v_fma_f32 v112, v115, s35, -v159
	v_fma_f32 v120, v120, s35, -v159
	v_fma_f32 v121, v121, s35, -v159
	v_fma_f32 v122, v122, s35, -v159
	v_fma_f32 v123, v123, s35, -v159
	v_fma_f32 v116, v116, s35, -v159
	v_fma_f32 v117, v117, s35, -v159
	v_fma_f32 v118, v118, s35, -v159
	v_fma_f32 v119, v119, s35, -v159
	v_exp_f32_e32 v135, v112
	v_mov_b64_e32 v[114:115], s[66:67]
	v_exp_f32_e32 v120, v120
	v_exp_f32_e32 v121, v121
	v_exp_f32_e32 v122, v122
	v_exp_f32_e32 v123, v123
	v_exp_f32_e32 v116, v116
	v_exp_f32_e32 v117, v117
	v_exp_f32_e32 v118, v118
	v_exp_f32_e32 v119, v119
	v_fma_f32 v108, v108, s35, -v159
	v_mov_b64_e32 v[112:113], s[64:65]
	v_exp_f32_e32 v136, v108
	v_fma_f32 v108, v109, s35, -v159
	v_exp_f32_e32 v137, v108
	v_fma_f32 v108, v110, s35, -v159
	v_exp_f32_e32 v138, v108
	v_fma_f32 v108, v111, s35, -v159
	v_exp_f32_e32 v139, v108
	v_cvt_pk_bf16_f32 v108, v120, v121
	v_cvt_pk_bf16_f32 v109, v122, v123
	v_cvt_pk_bf16_f32 v110, v116, v117
	v_cvt_pk_bf16_f32 v111, v118, v119
	v_cvt_pk_bf16_f32 v116, v132, v133
	v_cvt_pk_bf16_f32 v117, v134, v135
	s_setprio 1
	v_mfma_f32_16x16x32_bf16 v[64:67], v[112:115], v[108:111], v[64:67]
	v_cvt_pk_bf16_f32 v118, v136, v137
	v_cvt_pk_bf16_f32 v119, v138, v139
	s_nop 1
	v_mfma_f32_16x16x32_bf16 v[64:67], v[112:115], v[116:119], v[64:67]
	v_mfma_f32_16x16x32_bf16 v[36:39], v[112:115], v[124:127], v[36:39]
	v_mfma_f32_16x16x32_bf16 v[36:39], v[112:115], v[128:131], v[36:39]
	s_waitcnt lgkmcnt(7)
	v_mfma_f32_16x16x32_bf16 v[72:75], v[76:79], v[124:127], v[72:75]
	s_movk_i32 s65, 0x400
	v_mfma_f32_16x16x32_bf16 v[60:63], v[76:79], v[108:111], v[60:63]
	s_waitcnt lgkmcnt(6)
	v_mfma_f32_16x16x32_bf16 v[68:71], v[80:83], v[124:127], v[68:71]
	v_mfma_f32_16x16x32_bf16 v[48:51], v[80:83], v[108:111], v[48:51]
	s_waitcnt lgkmcnt(5)
	v_mfma_f32_16x16x32_bf16 v[56:59], v[84:87], v[124:127], v[56:59]
	v_mfma_f32_16x16x32_bf16 v[44:47], v[84:87], v[108:111], v[44:47]
	s_waitcnt lgkmcnt(4)
	v_mfma_f32_16x16x32_bf16 v[52:55], v[88:91], v[124:127], v[52:55]
	v_mfma_f32_16x16x32_bf16 v[40:43], v[88:91], v[108:111], v[40:43]
	s_waitcnt lgkmcnt(3)
	v_mfma_f32_16x16x32_bf16 v[72:75], v[92:95], v[128:131], v[72:75]
	v_mfma_f32_16x16x32_bf16 v[60:63], v[92:95], v[116:119], v[60:63]
	s_waitcnt lgkmcnt(2)
	v_mfma_f32_16x16x32_bf16 v[68:71], v[96:99], v[128:131], v[68:71]
	v_mfma_f32_16x16x32_bf16 v[48:51], v[96:99], v[116:119], v[48:51]
	s_waitcnt lgkmcnt(1)
	v_mfma_f32_16x16x32_bf16 v[56:59], v[100:103], v[128:131], v[56:59]
	v_mfma_f32_16x16x32_bf16 v[44:47], v[100:103], v[116:119], v[44:47]
	s_waitcnt lgkmcnt(0)
	v_mfma_f32_16x16x32_bf16 v[52:55], v[104:107], v[128:131], v[52:55]
	v_mfma_f32_16x16x32_bf16 v[40:43], v[104:107], v[116:119], v[40:43]
	s_setprio 0
	s_add_i32 s9, s6, -2
	s_cmp_ge_u32 s9, s5
	s_cbranch_scc0 .LBB0_1276

.LBB0_1291:
	v_fma_f32 v112, v112, s35, -v159
	v_fma_f32 v0, v120, s35, -v159
	v_fma_f32 v120, v121, s35, -v159
	v_fma_f32 v121, v122, s35, -v159
	v_fma_f32 v122, v123, s35, -v159
	v_exp_f32_e32 v123, v112
	v_fma_f32 v112, v113, s35, -v159
	v_exp_f32_e32 v132, v112
	v_fma_f32 v112, v114, s35, -v159
	v_exp_f32_e32 v133, v112
	v_fma_f32 v112, v115, s35, -v159
	v_fma_f32 v116, v116, s35, -v159
	v_fma_f32 v117, v117, s35, -v159
	v_fma_f32 v118, v118, s35, -v159
	v_fma_f32 v119, v119, s35, -v159
	v_exp_f32_e32 v134, v112
	v_mov_b64_e32 v[114:115], s[66:67]
	v_exp_f32_e32 v0, v0
	v_exp_f32_e32 v120, v120
	v_exp_f32_e32 v121, v121
	v_exp_f32_e32 v122, v122
	v_exp_f32_e32 v116, v116
	v_exp_f32_e32 v117, v117
	v_exp_f32_e32 v118, v118
	v_exp_f32_e32 v119, v119
	v_fma_f32 v108, v108, s35, -v159
	v_mov_b64_e32 v[112:113], s[64:65]
	v_exp_f32_e32 v135, v108
	v_fma_f32 v108, v109, s35, -v159
	v_exp_f32_e32 v136, v108
	v_fma_f32 v108, v110, s35, -v159
	v_exp_f32_e32 v137, v108
	v_fma_f32 v108, v111, s35, -v159
	v_exp_f32_e32 v138, v108
	v_cvt_pk_bf16_f32 v108, v0, v120
	v_cvt_pk_bf16_f32 v109, v121, v122
	v_cvt_pk_bf16_f32 v110, v116, v117
	v_cvt_pk_bf16_f32 v111, v118, v119
	v_cvt_pk_bf16_f32 v116, v123, v132
	v_cvt_pk_bf16_f32 v117, v133, v134
	s_setprio 1
	v_mfma_f32_16x16x32_bf16 v[64:67], v[112:115], v[108:111], v[64:67]
	v_cvt_pk_bf16_f32 v118, v135, v136
	v_cvt_pk_bf16_f32 v119, v137, v138
	s_nop 1
	v_mfma_f32_16x16x32_bf16 v[64:67], v[112:115], v[116:119], v[64:67]
	v_mfma_f32_16x16x32_bf16 v[36:39], v[112:115], v[124:127], v[36:39]
	v_mfma_f32_16x16x32_bf16 v[36:39], v[112:115], v[128:131], v[36:39]
	s_waitcnt lgkmcnt(7)
	v_mfma_f32_16x16x32_bf16 v[72:75], v[76:79], v[124:127], v[72:75]
	s_movk_i32 s65, 0x400
	v_mfma_f32_16x16x32_bf16 v[60:63], v[76:79], v[108:111], v[60:63]
	s_waitcnt lgkmcnt(6)
	v_mfma_f32_16x16x32_bf16 v[68:71], v[80:83], v[124:127], v[68:71]
	v_mfma_f32_16x16x32_bf16 v[48:51], v[80:83], v[108:111], v[48:51]
	s_waitcnt lgkmcnt(5)
	v_mfma_f32_16x16x32_bf16 v[56:59], v[84:87], v[124:127], v[56:59]
	v_mfma_f32_16x16x32_bf16 v[44:47], v[84:87], v[108:111], v[44:47]
	s_waitcnt lgkmcnt(4)
	v_mfma_f32_16x16x32_bf16 v[52:55], v[88:91], v[124:127], v[52:55]
	v_mfma_f32_16x16x32_bf16 v[40:43], v[88:91], v[108:111], v[40:43]
	s_waitcnt lgkmcnt(3)
	v_mfma_f32_16x16x32_bf16 v[72:75], v[92:95], v[128:131], v[72:75]
	v_mfma_f32_16x16x32_bf16 v[60:63], v[92:95], v[116:119], v[60:63]
	s_waitcnt lgkmcnt(2)
	v_mfma_f32_16x16x32_bf16 v[68:71], v[96:99], v[128:131], v[68:71]
	v_mfma_f32_16x16x32_bf16 v[48:51], v[96:99], v[116:119], v[48:51]
	s_waitcnt lgkmcnt(1)
	v_mfma_f32_16x16x32_bf16 v[56:59], v[100:103], v[128:131], v[56:59]
	v_mfma_f32_16x16x32_bf16 v[44:47], v[100:103], v[116:119], v[44:47]
	s_waitcnt lgkmcnt(0)
	v_mfma_f32_16x16x32_bf16 v[52:55], v[104:107], v[128:131], v[52:55]
	v_mfma_f32_16x16x32_bf16 v[40:43], v[104:107], v[116:119], v[40:43]
	s_setprio 0
	s_andn2_b64 vcc, exec, s[2:3]
	s_cbranch_vccz .LBB0_1287
	s_branch .LBB0_1288
